# accumulator zeroing at each GEMM unit start with 64 v_mov_b64 instead of 128 v_mov_b32 (G1, G2, G3)
# speedup vs baseline: 1.0023x; 1.0023x over previous
.LBB0_490:
	v_mov_b64_e32 v[2:3], s[26:27]
	s_ashr_i32 s41, s40, 31
	v_cmp_lt_i64_e32 vcc, s[16:17], v[2:3]
	s_lshl_b64 s[16:17], s[40:41], 19
	s_add_u32 s44, s46, s16
	s_addc_u32 s45, s47, s17
	s_and_b64 s[16:17], vcc, exec
	s_cselect_b32 s9, s45, s13
	s_cselect_b32 s11, s44, s12
	s_ashr_i32 s39, s38, 31
	s_lshl_b64 s[16:17], s[38:39], 19
	s_add_u32 s54, s71, s16
	s_addc_u32 s55, s73, s17
	s_and_b64 s[16:17], vcc, exec
	s_cselect_b32 s39, s55, s15
	s_cselect_b32 s41, s54, s14
	s_add_u32 s12, s12, 0x40080
	s_addc_u32 s13, s13, 0
	s_add_u32 s62, s14, 0x100
	v_mov_b64_e32 v[62:63], 0
	s_addc_u32 s63, s15, 0
	s_mov_b32 s64, -2
	v_mov_b64_e32 v[64:65], 0
	v_mov_b64_e32 v[66:67], 0
	v_mov_b64_e32 v[68:69], 0
	v_mov_b64_e32 v[78:79], 0
	v_mov_b64_e32 v[80:81], 0
	v_mov_b64_e32 v[82:83], 0
	v_mov_b64_e32 v[84:85], 0
	v_mov_b64_e32 v[94:95], 0
	v_mov_b64_e32 v[96:97], 0
	v_mov_b64_e32 v[98:99], 0
	v_mov_b64_e32 v[100:101], 0
	v_mov_b64_e32 v[110:111], 0
	v_mov_b64_e32 v[112:113], 0
	v_mov_b64_e32 v[114:115], 0
	v_mov_b64_e32 v[116:117], 0
	v_mov_b64_e32 v[70:71], 0
	v_mov_b64_e32 v[72:73], 0
	v_mov_b64_e32 v[74:75], 0
	v_mov_b64_e32 v[76:77], 0
	v_mov_b64_e32 v[86:87], 0
	v_mov_b64_e32 v[88:89], 0
	v_mov_b64_e32 v[90:91], 0
	v_mov_b64_e32 v[92:93], 0
	v_mov_b64_e32 v[102:103], 0
	v_mov_b64_e32 v[104:105], 0
	v_mov_b64_e32 v[106:107], 0
	v_mov_b64_e32 v[108:109], 0
	v_mov_b64_e32 v[118:119], 0
	v_mov_b64_e32 v[120:121], 0
	v_mov_b64_e32 v[122:123], 0
	v_mov_b64_e32 v[124:125], 0
	v_mov_b64_e32 v[126:127], 0
	v_mov_b64_e32 v[128:129], 0
	v_mov_b64_e32 v[130:131], 0
	v_mov_b64_e32 v[132:133], 0
	v_mov_b64_e32 v[142:143], 0
	v_mov_b64_e32 v[144:145], 0
	v_mov_b64_e32 v[146:147], 0
	v_mov_b64_e32 v[148:149], 0
	v_mov_b64_e32 v[166:167], 0
	v_mov_b64_e32 v[168:169], 0
	v_mov_b64_e32 v[170:171], 0
	v_mov_b64_e32 v[172:173], 0
	v_mov_b64_e32 v[190:191], 0
	v_mov_b64_e32 v[192:193], 0
	v_mov_b64_e32 v[194:195], 0
	v_mov_b64_e32 v[196:197], 0
	v_mov_b64_e32 v[134:135], 0
	v_mov_b64_e32 v[136:137], 0
	v_mov_b64_e32 v[138:139], 0
	v_mov_b64_e32 v[140:141], 0
	v_mov_b64_e32 v[154:155], 0
	v_mov_b64_e32 v[156:157], 0
	v_mov_b64_e32 v[158:159], 0
	v_mov_b64_e32 v[160:161], 0
	v_mov_b64_e32 v[178:179], 0
	v_mov_b64_e32 v[180:181], 0
	v_mov_b64_e32 v[182:183], 0
	v_mov_b64_e32 v[184:185], 0
	v_mov_b64_e32 v[198:199], 0
	v_mov_b64_e32 v[200:201], 0
	v_mov_b64_e32 v[202:203], 0
	v_mov_b64_e32 v[204:205], 0

.LBB0_860:
	s_add_u32 vcc_lo, s12, 0x100
	v_mov_b64_e32 v[62:63], 0
	s_addc_u32 vcc_hi, s13, 0
	s_mov_b32 s8, 0
	v_mov_b64_e32 v[64:65], 0
	v_mov_b64_e32 v[66:67], 0
	v_mov_b64_e32 v[68:69], 0
	v_mov_b64_e32 v[74:75], 0
	v_mov_b64_e32 v[76:77], 0
	v_mov_b64_e32 v[82:83], 0
	v_mov_b64_e32 v[84:85], 0
	v_mov_b64_e32 v[90:91], 0
	v_mov_b64_e32 v[92:93], 0
	v_mov_b64_e32 v[98:99], 0
	v_mov_b64_e32 v[100:101], 0
	v_mov_b64_e32 v[106:107], 0
	v_mov_b64_e32 v[108:109], 0
	v_mov_b64_e32 v[114:115], 0
	v_mov_b64_e32 v[116:117], 0
	v_mov_b64_e32 v[70:71], 0
	v_mov_b64_e32 v[72:73], 0
	v_mov_b64_e32 v[78:79], 0
	v_mov_b64_e32 v[80:81], 0
	v_mov_b64_e32 v[86:87], 0
	v_mov_b64_e32 v[88:89], 0
	v_mov_b64_e32 v[94:95], 0
	v_mov_b64_e32 v[96:97], 0
	v_mov_b64_e32 v[102:103], 0
	v_mov_b64_e32 v[104:105], 0
	v_mov_b64_e32 v[110:111], 0
	v_mov_b64_e32 v[112:113], 0
	v_mov_b64_e32 v[118:119], 0
	v_mov_b64_e32 v[120:121], 0
	v_mov_b64_e32 v[122:123], 0
	v_mov_b64_e32 v[124:125], 0
	v_mov_b64_e32 v[126:127], 0
	v_mov_b64_e32 v[128:129], 0
	v_mov_b64_e32 v[130:131], 0
	v_mov_b64_e32 v[132:133], 0
	v_mov_b64_e32 v[142:143], 0
	v_mov_b64_e32 v[144:145], 0
	v_mov_b64_e32 v[146:147], 0
	v_mov_b64_e32 v[148:149], 0
	v_mov_b64_e32 v[158:159], 0
	v_mov_b64_e32 v[160:161], 0
	v_mov_b64_e32 v[162:163], 0
	v_mov_b64_e32 v[164:165], 0
	v_mov_b64_e32 v[182:183], 0
	v_mov_b64_e32 v[184:185], 0
	v_mov_b64_e32 v[186:187], 0
	v_mov_b64_e32 v[188:189], 0
	v_mov_b64_e32 v[134:135], 0
	v_mov_b64_e32 v[136:137], 0
	v_mov_b64_e32 v[138:139], 0
	v_mov_b64_e32 v[140:141], 0
	v_mov_b64_e32 v[150:151], 0
	v_mov_b64_e32 v[152:153], 0
	v_mov_b64_e32 v[154:155], 0
	v_mov_b64_e32 v[156:157], 0
	v_mov_b64_e32 v[170:171], 0
	v_mov_b64_e32 v[172:173], 0
	v_mov_b64_e32 v[178:179], 0
	v_mov_b64_e32 v[180:181], 0
	v_mov_b64_e32 v[198:199], 0
	v_mov_b64_e32 v[200:201], 0
	v_mov_b64_e32 v[202:203], 0
	v_mov_b64_e32 v[204:205], 0

.LBB0_1151:
	v_mov_b64_e32 v[2:3], 0x200
	s_ashr_i32 s13, s12, 31
	v_cmp_lt_i64_e32 vcc, s[14:15], v[2:3]
	s_lshl_b64 s[14:15], s[12:13], 19
	s_add_u32 s14, s80, s14
	s_addc_u32 s15, s83, s15
	s_and_b64 s[16:17], vcc, exec
	s_cselect_b32 s13, s15, s7
	s_cselect_b32 s54, s14, s6
	s_ashr_i32 s11, s10, 31
	s_lshl_b64 s[16:17], s[10:11], 19
	s_add_u32 s16, s23, s16
	s_addc_u32 s17, s36, s17
	s_and_b64 s[26:27], vcc, exec
	s_cselect_b32 s11, s17, s9
	s_cselect_b32 s55, s16, s8
	s_add_u32 s6, s6, 0x40080
	s_addc_u32 s7, s7, 0
	s_add_u32 s56, s8, 0x100
	v_mov_b64_e32 v[78:79], 0
	s_addc_u32 s57, s9, 0
	s_mov_b32 s58, -2
	v_mov_b64_e32 v[80:81], 0
	v_mov_b64_e32 v[82:83], 0
	v_mov_b64_e32 v[84:85], 0
	v_mov_b64_e32 v[94:95], 0
	v_mov_b64_e32 v[96:97], 0
	v_mov_b64_e32 v[98:99], 0
	v_mov_b64_e32 v[100:101], 0
	v_mov_b64_e32 v[110:111], 0
	v_mov_b64_e32 v[112:113], 0
	v_mov_b64_e32 v[114:115], 0
	v_mov_b64_e32 v[116:117], 0
	v_mov_b64_e32 v[126:127], 0
	v_mov_b64_e32 v[128:129], 0
	v_mov_b64_e32 v[130:131], 0
	v_mov_b64_e32 v[132:133], 0
	v_mov_b64_e32 v[86:87], 0
	v_mov_b64_e32 v[88:89], 0
	v_mov_b64_e32 v[90:91], 0
	v_mov_b64_e32 v[92:93], 0
	v_mov_b64_e32 v[102:103], 0
	v_mov_b64_e32 v[104:105], 0
	v_mov_b64_e32 v[106:107], 0
	v_mov_b64_e32 v[108:109], 0
	v_mov_b64_e32 v[118:119], 0
	v_mov_b64_e32 v[120:121], 0
	v_mov_b64_e32 v[122:123], 0
	v_mov_b64_e32 v[124:125], 0
	v_mov_b64_e32 v[134:135], 0
	v_mov_b64_e32 v[136:137], 0
	v_mov_b64_e32 v[138:139], 0
	v_mov_b64_e32 v[140:141], 0
	v_mov_b64_e32 v[142:143], 0
	v_mov_b64_e32 v[144:145], 0
	v_mov_b64_e32 v[146:147], 0
	v_mov_b64_e32 v[148:149], 0
	v_mov_b64_e32 v[158:159], 0
	v_mov_b64_e32 v[160:161], 0
	v_mov_b64_e32 v[162:163], 0
	v_mov_b64_e32 v[164:165], 0
	v_mov_b64_e32 v[174:175], 0
	v_mov_b64_e32 v[176:177], 0
	v_mov_b64_e32 v[178:179], 0
	v_mov_b64_e32 v[180:181], 0
	v_mov_b64_e32 v[190:191], 0
	v_mov_b64_e32 v[192:193], 0
	v_mov_b64_e32 v[194:195], 0
	v_mov_b64_e32 v[196:197], 0
	v_mov_b64_e32 v[150:151], 0
	v_mov_b64_e32 v[152:153], 0
	v_mov_b64_e32 v[154:155], 0
	v_mov_b64_e32 v[156:157], 0
	v_mov_b64_e32 v[166:167], 0
	v_mov_b64_e32 v[168:169], 0
	v_mov_b64_e32 v[170:171], 0
	v_mov_b64_e32 v[172:173], 0
	v_mov_b64_e32 v[182:183], 0
	v_mov_b64_e32 v[184:185], 0
	v_mov_b64_e32 v[186:187], 0
	v_mov_b64_e32 v[188:189], 0
	v_mov_b64_e32 v[198:199], 0
	v_mov_b64_e32 v[200:201], 0
	v_mov_b64_e32 v[202:203], 0
	v_mov_b64_e32 v[204:205], 0
